# 4-workgroup seams everywhere except S0/S4/S5, with arrival counters guarding the ACT/QKVUZG buffer overlay (checked before the first P4/P9 epilogue); 30us stagger
# speedup vs baseline: 1.0103x; 1.0103x over previous
; __device__ __forceinline__ unsigned xb_ld(unsigned* p)              { return __hip_atomic_load(p, __ATOMIC_RELAXED, __HIP_MEMORY_SCOPE_AGENT); }
; __device__ __forceinline__ unsigned xb_add(unsigned* p, unsigned v) { return __hip_atomic_fetch_add(p, v, __ATOMIC_RELAXED, __HIP_MEMORY_SCOPE_AGENT); }
; #define XB_SPIN(cond, bar) do { unsigned _sp = 0; while (cond) { __builtin_amdgcn_s_sleep(1); \
;     if ((++_sp & 255u) == 0u) { if (xb_ld(&(bar)[XB_TMO])) break; if (_sp > XB_SPIN_CAP) { atomicAdd(&(bar)[XB_TMO], 1u); break; } } } } while (0)
; __device__ __forceinline__ void xcd_barrier(const XcdBarrier& b) {
;     asm volatile("s_waitcnt vmcnt(0)" ::: "memory");
;     __syncthreads();
;     if (threadIdx.x == 0) {
;         unsigned* bar = b.bar;
;         __builtin_amdgcn_s_waitcnt(0);
;         unsigned nloc = b.st[0], nx = b.st[1];
;         if (nloc == 0u) { xcd_barrier_complete(bar, b.x, nloc, nx); b.st[0] = nloc; b.st[1] = nx; }
;         const unsigned old = xb_add(&bar[XB_XSUB(b.x)], 1u);
;         const unsigned gen = old / nloc;
;         if (old + 1u == (gen + 1u) * nloc) {
;             __builtin_amdgcn_fence(__ATOMIC_RELEASE, "agent");
;             asm volatile("s_waitcnt vmcnt(0)" ::: "memory");
;             const unsigned og = xb_add(&bar[XB_TOP], 1u);
;             const unsigned tg = og / nx;
;             if (og + 1u == (tg + 1u) * nx) xb_add(&bar[XB_TOPGEN], 1u);
;             else XB_SPIN(xb_ld(&bar[XB_TOPGEN]) == tg, bar);
;             __builtin_amdgcn_fence(__ATOMIC_ACQUIRE, "agent");
;             xb_add(&bar[XB_XGEN(b.x)], 1u);
;             asm volatile("s_waitcnt vmcnt(0)" ::: "memory");
;         } else {
;             XB_SPIN(xb_ld(&bar[XB_XGEN(b.x)]) == gen, bar);
;             __builtin_amdgcn_fence(__ATOMIC_ACQUIRE, "agent");
;             asm volatile("s_waitcnt vmcnt(0)" ::: "memory");
;         }
;     }
;     __syncthreads();
; }
.LBB0_202:
	v_readlane_b32 s0, v254, 0
	v_readlane_b32 s1, v254, 1
	s_cmp_gt_u32 s1, 3
	s_cselect_b64 s[0:1], -1, 0
	s_and_b64 s[0:1], s[6:7], s[0:1]
	s_andn2_b64 vcc, exec, s[0:1]
	s_cbranch_vccnz .LBB0_252
	s_waitcnt vmcnt(0)
	v_cmp_eq_u32_e32 vcc, 0, v189
	s_waitcnt vmcnt(8)
	s_barrier
	s_and_saveexec_b64 s[0:1], vcc
	s_cbranch_execz .LBB0_251
	v_mov_b32_e32 v0, 0x20430
	ds_read_b32 v0, v0
	s_waitcnt lgkmcnt(0)
	v_cmp_ne_u32_e32 vcc, 0, v0
	s_cbranch_vccz .Lseam_slow_2
	v_readlane_b32 s8, v255, 0
	v_readlane_b32 s2, v254, 4
	v_readlane_b32 s3, v254, 5
	s_and_b32 s8, s8, 63
	s_lshl_b32 s8, s8, 2
	s_add_i32 s8, s8, 0x100
	v_mov_b32_e32 v0, s8
	v_mov_b32_e32 v1, 1
	s_mov_b32 s9, 0
	s_nop 2
	global_atomic_add v0, v1, s[2:3]
	v_mov_b32_e32 v2, 0
	global_atomic_add v2, v1, s[2:3] offset:768

; template <class Epi, class Sched, bool ALIGN_EPI = false, bool SP2 = false>
; __device__ __forceinline__ void gemm_phase(PG8_LAS unsigned char* lds, const Gemm g, const Sched& S, const Epi& E) {
;     ...
;         if constexpr (!Epi::AFTER_DRAIN) { E(acc, cur, wr, wc, fr, fq); S.done(cur); }
;     __device__ __forceinline__ void operator()(const f32x4 (&acc)[2][2][4][2], const Unit& u, int wr, int wc, int fr, int fq) const {
;         const int pn = u.pn; int row0 = u.pm * BM + wr * 64 + fr, cin = wc * 32 + 8 * fq, rl0 = wr * 64 + fr;
;         asm volatile("" : "+v"(row0), "+v"(cin), "+v"(rl0));
;         if (pn < 4) body<0>(acc, Q + pn * BM, 1024, row0, cin, rl0, fq, nullptr, nullptr);
;         else if (pn < 6) body<0>(acc, pn == 4 ? K : V, 256, row0, cin, rl0, fq, nullptr, nullptr);
;         else if (pn < 10) body<1>(acc, U + (pn - 6) * BM, 1024, row0, cin, rl0, fq, nullptr, nullptr);
;         else if (pn < 14) body<2>(acc, Z + (pn - 10) * BM, 1024, row0, cin, rl0, fq, nullptr, stats + ((pn - 10) * 4 + wc) * 2);
;         else body<3>(acc, G + (pn - 14) * BM, 4096, row0, cin, rl0, fq, gbias + (pn - 14) * BM + cin, nullptr);
;     }
.LBB0_271:
	v_mov_b32_e32 v202, 0x20430
	ds_read2_b32 v[202:203], v202 offset1:1
	s_waitcnt lgkmcnt(0)
	v_cmp_eq_u32_e32 vcc, 0, v202
	s_cbranch_vccnz .Lgw4_done
	v_cmp_ne_u32_e32 vcc, 0, v203
	s_cbranch_vccnz .Lgw4_done
	v_mov_b32_e32 v202, 0
.Lgw4_loop:
	v_readlane_b32 vcc_lo, v254, 4
	v_readlane_b32 vcc_hi, v254, 5
	s_nop 4
	global_load_dword v204, v202, vcc offset:768 sc1
	s_waitcnt vmcnt(0)
	v_cmp_gt_u32_e32 vcc, 0x100, v204
	s_cbranch_vccz .Lgw4_ok
	s_sleep 2
	s_branch .Lgw4_loop
.Lgw4_ok:
	v_mov_b32_e32 v202, 0x20434
	v_mov_b32_e32 v204, 1
	ds_write_b32 v202, v204

; __device__ __forceinline__ unsigned xb_ld(unsigned* p)              { return __hip_atomic_load(p, __ATOMIC_RELAXED, __HIP_MEMORY_SCOPE_AGENT); }
; __device__ __forceinline__ unsigned xb_add(unsigned* p, unsigned v) { return __hip_atomic_fetch_add(p, v, __ATOMIC_RELAXED, __HIP_MEMORY_SCOPE_AGENT); }
; #define XB_SPIN(cond, bar) do { unsigned _sp = 0; while (cond) { __builtin_amdgcn_s_sleep(1); \
;     if ((++_sp & 255u) == 0u) { if (xb_ld(&(bar)[XB_TMO])) break; if (_sp > XB_SPIN_CAP) { atomicAdd(&(bar)[XB_TMO], 1u); break; } } } } while (0)
; __device__ __forceinline__ void xcd_barrier(const XcdBarrier& b) {
;     asm volatile("s_waitcnt vmcnt(0)" ::: "memory");
;     __syncthreads();
;     if (threadIdx.x == 0) {
;         unsigned* bar = b.bar;
;         __builtin_amdgcn_s_waitcnt(0);
;         unsigned nloc = b.st[0], nx = b.st[1];
;         if (nloc == 0u) { xcd_barrier_complete(bar, b.x, nloc, nx); b.st[0] = nloc; b.st[1] = nx; }
;         const unsigned old = xb_add(&bar[XB_XSUB(b.x)], 1u);
;         const unsigned gen = old / nloc;
;         if (old + 1u == (gen + 1u) * nloc) {
;             __builtin_amdgcn_fence(__ATOMIC_RELEASE, "agent");
;             asm volatile("s_waitcnt vmcnt(0)" ::: "memory");
;             const unsigned og = xb_add(&bar[XB_TOP], 1u);
;             const unsigned tg = og / nx;
;             if (og + 1u == (tg + 1u) * nx) xb_add(&bar[XB_TOPGEN], 1u);
;             else XB_SPIN(xb_ld(&bar[XB_TOPGEN]) == tg, bar);
;             __builtin_amdgcn_fence(__ATOMIC_ACQUIRE, "agent");
;             xb_add(&bar[XB_XGEN(b.x)], 1u);
;             asm volatile("s_waitcnt vmcnt(0)" ::: "memory");
;         } else {
;             XB_SPIN(xb_ld(&bar[XB_XGEN(b.x)]) == gen, bar);
;             __builtin_amdgcn_fence(__ATOMIC_ACQUIRE, "agent");
;             asm volatile("s_waitcnt vmcnt(0)" ::: "memory");
;         }
;     }
;     __syncthreads();
; }
.LBB0_513:
	s_cmp_gt_i32 s75, 7
	s_cselect_b64 s[0:1], -1, 0
	s_and_b64 s[2:3], s[8:9], s[0:1]
	s_andn2_b64 vcc, exec, s[2:3]
	s_cbranch_vccnz .LBB0_563
	s_waitcnt vmcnt(0)
	v_cmp_eq_u32_e32 vcc, 0, v189
	s_waitcnt vmcnt(0) lgkmcnt(0)
	s_barrier
	s_and_saveexec_b64 s[4:5], vcc
	s_cbranch_execz .LBB0_562
	v_mov_b32_e32 v0, 0x20430
	ds_read_b32 v0, v0
	s_waitcnt lgkmcnt(0)
	v_cmp_ne_u32_e32 vcc, 0, v0
	s_cbranch_vccz .Lseam_slow_5
	v_readlane_b32 s8, v255, 0
	v_readlane_b32 s2, v254, 4
	v_readlane_b32 s3, v254, 5
	s_and_b32 s8, s8, 63
	s_lshl_b32 s8, s8, 2
	s_add_i32 s8, s8, 0x100
	v_mov_b32_e32 v0, s8
	v_mov_b32_e32 v1, 1
	s_mov_b32 s9, 0
	s_nop 2
	global_atomic_add v0, v1, s[2:3]
	v_mov_b32_e32 v2, 0
	global_atomic_add v2, v1, s[2:3] offset:896

; __device__ __forceinline__ unsigned cvt_pk_bf16(float lo, float hi) { typedef float f2_t __attribute__((ext_vector_type(2))); typedef __bf16 b2_t __attribute__((ext_vector_type(2))); const f2_t v = {lo, hi}; return __builtin_bit_cast(unsigned, __builtin_convertvector(v, b2_t)); }
; __device__ __forceinline__ float silu_f(float x) { return x * sigm(x); }
;     __device__ __forceinline__ void operator()(const f32x4 (&acc)[2][2][4][2], const Unit& u, int wr, int wc, int fr, int fq) const {
;         const int row0 = u.pm * BM + wr * 64 + fr, col0 = u.pn * HALF + wc * 32 + 8 * fq;
; #pragma unroll
;         for (int ai = 0; ai < 2; ++ai)
; #pragma unroll
;             for (int m = 0; m < 4; ++m) {
;                 bf16_t* rowp = O + (size_t)(row0 + ai * HALF + m * 16) * ldc + col0;
;                 f32x4 g0 = acc[ai][0][m][0], g1 = acc[ai][0][m][1], u0 = acc[ai][1][m][0], u1 = acc[ai][1][m][1];
;                 if (SCALED) { const float r = rs[ai * HALF + wr * 64 + m * 16 + fr]; g0 = g0 * r; g1 = g1 * r; u0 = u0 * r; u1 = u1 * r; }
;                 u32x4 w;
;                 w.x = cvt_pk_bf16(silu_f(g0[0]) * u0[0], silu_f(g0[1]) * u0[1]); w.y = cvt_pk_bf16(silu_f(g0[2]) * u0[2], silu_f(g0[3]) * u0[3]);
;                 w.z = cvt_pk_bf16(silu_f(g1[0]) * u1[0], silu_f(g1[1]) * u1[1]); w.w = cvt_pk_bf16(silu_f(g1[2]) * u1[2], silu_f(g1[3]) * u1[3]);
;                 *(u32x4*)rowp = w;
;             }
.LBB0_657:
	v_mov_b32_e32 v244, 0x20430
	ds_read2_b32 v[244:245], v244 offset1:2
	s_waitcnt lgkmcnt(0)
	v_cmp_eq_u32_e32 vcc, 0, v244
	s_cbranch_vccnz .Lgw9_done
	v_cmp_ne_u32_e32 vcc, 0, v245
	s_cbranch_vccnz .Lgw9_done
	v_mov_b32_e32 v244, 0
.Lgw9_loop:
	v_readlane_b32 vcc_lo, v254, 4
	v_readlane_b32 vcc_hi, v254, 5
	s_nop 4
	global_load_dword v246, v244, vcc offset:896 sc1
	s_waitcnt vmcnt(0)
	v_cmp_gt_u32_e32 vcc, 0x100, v246
	s_cbranch_vccz .Lgw9_ok
	s_sleep 2
	s_branch .Lgw9_loop
.Lgw9_ok:
	v_mov_b32_e32 v244, 0x20438
	v_mov_b32_e32 v246, 1
	ds_write_b32 v244, v246
